# LDS-DMA attention loop: M0-early DMA issue combined with two row-sum accumulators
# baseline (speedup 1.0000x reference)
.Lattn_nf_loop:
	ds_read_b128 v[98:101], v82 offset:0
	ds_read_b128 v[102:105], v83 offset:0
	ds_read_b128 v[106:109], v84 offset:0
	ds_read_b128 v[110:113], v85 offset:0
	s_and_b32 s10, s15, 1
	s_xor_b32 s10, s10, 1
	s_lshl_b32 s10, s10, 15
	s_add_i32 s10, s10, s11
	s_add_i32 s6, s10, 0x10000
	s_add_i32 m0, s10, 0x0
	s_waitcnt lgkmcnt(3)
	v_mfma_f32_32x32x16_bf16 v[138:153], v[98:101], v[10:13], 0
	ds_read_b128 v[98:101], v82 offset:8192
	global_load_lds_dwordx4 v124, s[64:65]
	s_add_i32 m0, s10, 0x2000
	s_waitcnt lgkmcnt(3)
	v_mfma_f32_32x32x16_bf16 v[138:153], v[102:105], v[14:17], v[138:153]
	ds_read_b128 v[102:105], v83 offset:8192
	global_load_lds_dwordx4 v124, s[66:67]
	s_add_i32 m0, s10, 0x4000
	s_waitcnt lgkmcnt(3)
	v_mfma_f32_32x32x16_bf16 v[138:153], v[106:109], v[2:5], v[138:153]
	ds_read_b128 v[106:109], v84 offset:8192
	global_load_lds_dwordx4 v124, s[68:69]
	s_add_i32 m0, s10, 0x6000
	s_waitcnt lgkmcnt(3)
	v_mfma_f32_32x32x16_bf16 v[138:153], v[110:113], v[6:9], v[138:153]
	ds_read_b128 v[110:113], v85 offset:8192
	global_load_lds_dwordx4 v124, s[70:71]
	v_add_u32_e32 v124, s36, v124
	s_add_i32 m0, s6, 0x0
	s_waitcnt lgkmcnt(3)
	v_mfma_f32_32x32x16_bf16 v[154:169], v[98:101], v[10:13], 0
	ds_read_b128 v[98:101], v82 offset:16384
	global_load_lds_dwordx4 v125, s[72:73]
	ds_read_b128 v[128:131], v86 offset:0
	ds_read_b128 v[184:187], v86 offset:8192
	s_nop 1
	v_exp_f32_e32 v138, v138
	v_exp_f32_e32 v139, v139
	v_exp_f32_e32 v140, v140
	v_exp_f32_e32 v141, v141
	v_exp_f32_e32 v142, v142
	v_exp_f32_e32 v143, v143
	s_add_i32 m0, s6, 0x2000
	s_waitcnt lgkmcnt(5)
	v_mfma_f32_32x32x16_bf16 v[154:169], v[102:105], v[14:17], v[154:169]
	ds_read_b128 v[102:105], v83 offset:16384
	global_load_lds_dwordx4 v125, s[74:75]
	ds_read_b128 v[188:191], v86 offset:16384
	ds_read_b128 v[192:195], v86 offset:24576
	v_exp_f32_e32 v144, v144
	v_exp_f32_e32 v145, v145
	v_add_f32_e32 v122, v138, v122
	v_add_f32_e32 v123, v139, v123
	v_add_f32_e32 v122, v140, v122
	v_add_f32_e32 v123, v141, v123
	v_add_f32_e32 v122, v142, v122
	v_add_f32_e32 v123, v143, v123
	v_add_f32_e32 v122, v144, v122
	v_add_f32_e32 v123, v145, v123
	v_cvt_pk_bf16_f32 v114, v138, v139
	v_cvt_pk_bf16_f32 v115, v140, v141
	v_cvt_pk_bf16_f32 v116, v142, v143
	v_cvt_pk_bf16_f32 v117, v144, v145
	s_add_i32 m0, s6, 0x4000
	s_waitcnt lgkmcnt(7)
	v_mfma_f32_32x32x16_bf16 v[154:169], v[106:109], v[2:5], v[154:169]
	ds_read_b128 v[106:109], v84 offset:16384
	global_load_lds_dwordx4 v125, s[76:77]
	ds_read_b128 v[196:199], v87 offset:0
	v_exp_f32_e32 v146, v146
	v_exp_f32_e32 v147, v147
	s_add_i32 m0, s6, 0x6000
	s_waitcnt lgkmcnt(8)
	v_mfma_f32_32x32x16_bf16 v[154:169], v[110:113], v[6:9], v[154:169]
	ds_read_b128 v[110:113], v85 offset:16384
	global_load_lds_dwordx4 v125, s[78:79]
	v_add_u32_e32 v125, s38, v125
	ds_read_b128 v[216:219], v87 offset:8192
	v_exp_f32_e32 v148, v148
	v_exp_f32_e32 v149, v149
	s_waitcnt lgkmcnt(8)
	v_mfma_f32_32x32x16_bf16 v[18:33], v[128:131], v[114:117], v[18:33]
	v_exp_f32_e32 v150, v150
	v_exp_f32_e32 v151, v151
	s_waitcnt lgkmcnt(7)
	v_mfma_f32_32x32x16_bf16 v[34:49], v[184:187], v[114:117], v[34:49]
	ds_read_b128 v[200:203], v87 offset:16384
	v_exp_f32_e32 v152, v152
	v_exp_f32_e32 v153, v153
	s_waitcnt lgkmcnt(6)
	v_mfma_f32_32x32x16_bf16 v[50:65], v[188:191], v[114:117], v[50:65]
	ds_read_b128 v[204:207], v87 offset:24576
	v_add_f32_e32 v122, v146, v122
	v_add_f32_e32 v123, v147, v123
	v_add_f32_e32 v122, v148, v122
	v_add_f32_e32 v123, v149, v123
	s_waitcnt lgkmcnt(6)
	v_mfma_f32_32x32x16_bf16 v[66:81], v[192:195], v[114:117], v[66:81]
	v_add_f32_e32 v122, v150, v122
	v_add_f32_e32 v123, v151, v123
	v_add_f32_e32 v122, v152, v122
	v_add_f32_e32 v123, v153, v123
	v_cvt_pk_bf16_f32 v118, v146, v147
	v_cvt_pk_bf16_f32 v119, v148, v149
	v_cvt_pk_bf16_f32 v120, v150, v151
	v_cvt_pk_bf16_f32 v121, v152, v153
	v_mfma_f32_32x32x16_bf16 v[138:153], v[98:101], v[10:13], 0
	ds_read_b128 v[98:101], v82 offset:24576
	ds_read_b128 v[128:131], v88 offset:0
	v_exp_f32_e32 v154, v154
	v_exp_f32_e32 v155, v155
	v_mfma_f32_32x32x16_bf16 v[138:153], v[102:105], v[14:17], v[138:153]
	ds_read_b128 v[102:105], v83 offset:24576
	ds_read_b128 v[184:187], v88 offset:8192
	v_exp_f32_e32 v156, v156
	v_exp_f32_e32 v157, v157
	s_waitcnt lgkmcnt(8)
	v_mfma_f32_32x32x16_bf16 v[18:33], v[196:199], v[118:121], v[18:33]
	v_exp_f32_e32 v158, v158
	v_exp_f32_e32 v159, v159
	s_waitcnt lgkmcnt(6)
	v_mfma_f32_32x32x16_bf16 v[34:49], v[216:219], v[118:121], v[34:49]
	ds_read_b128 v[188:191], v88 offset:16384
	v_exp_f32_e32 v160, v160
	v_exp_f32_e32 v161, v161
	s_waitcnt lgkmcnt(6)
	v_mfma_f32_32x32x16_bf16 v[50:65], v[200:203], v[118:121], v[50:65]
	ds_read_b128 v[192:195], v88 offset:24576
	v_add_f32_e32 v122, v154, v122
	v_add_f32_e32 v123, v155, v123
	v_add_f32_e32 v122, v156, v122
	v_add_f32_e32 v123, v157, v123
	s_waitcnt lgkmcnt(6)
	v_mfma_f32_32x32x16_bf16 v[66:81], v[204:207], v[118:121], v[66:81]
	v_add_f32_e32 v122, v158, v122
	v_add_f32_e32 v123, v159, v123
	v_add_f32_e32 v122, v160, v122
	v_add_f32_e32 v123, v161, v123
	v_cvt_pk_bf16_f32 v114, v154, v155
	v_cvt_pk_bf16_f32 v115, v156, v157
	v_cvt_pk_bf16_f32 v116, v158, v159
	v_cvt_pk_bf16_f32 v117, v160, v161
	v_mfma_f32_32x32x16_bf16 v[138:153], v[106:109], v[2:5], v[138:153]
	ds_read_b128 v[106:109], v84 offset:24576
	ds_read_b128 v[196:199], v89 offset:0
	v_exp_f32_e32 v162, v162
	v_exp_f32_e32 v163, v163
	v_mfma_f32_32x32x16_bf16 v[138:153], v[110:113], v[6:9], v[138:153]
	ds_read_b128 v[110:113], v85 offset:24576
	ds_read_b128 v[216:219], v89 offset:8192
	v_exp_f32_e32 v164, v164
	v_exp_f32_e32 v165, v165
	s_waitcnt lgkmcnt(8)
	v_mfma_f32_32x32x16_bf16 v[18:33], v[128:131], v[114:117], v[18:33]
	v_exp_f32_e32 v166, v166
	v_exp_f32_e32 v167, v167
	s_waitcnt lgkmcnt(6)
	v_mfma_f32_32x32x16_bf16 v[34:49], v[184:187], v[114:117], v[34:49]
	ds_read_b128 v[200:203], v89 offset:16384
	v_exp_f32_e32 v168, v168
	v_exp_f32_e32 v169, v169
	s_waitcnt lgkmcnt(6)
	v_mfma_f32_32x32x16_bf16 v[50:65], v[188:191], v[114:117], v[50:65]
	ds_read_b128 v[204:207], v89 offset:24576
	v_add_f32_e32 v122, v162, v122
	v_add_f32_e32 v123, v163, v123
	v_add_f32_e32 v122, v164, v122
	v_add_f32_e32 v123, v165, v123
	s_waitcnt lgkmcnt(6)
	v_mfma_f32_32x32x16_bf16 v[66:81], v[192:195], v[114:117], v[66:81]
	v_add_f32_e32 v122, v166, v122
	v_add_f32_e32 v123, v167, v123
	v_add_f32_e32 v122, v168, v122
	v_add_f32_e32 v123, v169, v123
	v_cvt_pk_bf16_f32 v118, v162, v163
	v_cvt_pk_bf16_f32 v119, v164, v165
	v_cvt_pk_bf16_f32 v120, v166, v167
	v_cvt_pk_bf16_f32 v121, v168, v169
	v_mfma_f32_32x32x16_bf16 v[154:169], v[98:101], v[10:13], 0
	ds_read_b128 v[128:131], v90 offset:0
	v_exp_f32_e32 v138, v138
	v_exp_f32_e32 v139, v139
	v_mfma_f32_32x32x16_bf16 v[154:169], v[102:105], v[14:17], v[154:169]
	ds_read_b128 v[184:187], v90 offset:8192
	v_exp_f32_e32 v140, v140
	v_exp_f32_e32 v141, v141
	s_waitcnt lgkmcnt(6)
	v_mfma_f32_32x32x16_bf16 v[18:33], v[196:199], v[118:121], v[18:33]
	v_exp_f32_e32 v142, v142
	v_exp_f32_e32 v143, v143
	s_waitcnt lgkmcnt(4)
	v_mfma_f32_32x32x16_bf16 v[34:49], v[216:219], v[118:121], v[34:49]
	ds_read_b128 v[188:191], v90 offset:16384
	v_exp_f32_e32 v144, v144
	v_exp_f32_e32 v145, v145
	s_waitcnt lgkmcnt(4)
	v_mfma_f32_32x32x16_bf16 v[50:65], v[200:203], v[118:121], v[50:65]
	ds_read_b128 v[192:195], v90 offset:24576
	v_add_f32_e32 v122, v138, v122
	v_add_f32_e32 v123, v139, v123
	v_add_f32_e32 v122, v140, v122
	v_add_f32_e32 v123, v141, v123
	s_waitcnt lgkmcnt(4)
	v_mfma_f32_32x32x16_bf16 v[66:81], v[204:207], v[118:121], v[66:81]
	v_add_f32_e32 v122, v142, v122
	v_add_f32_e32 v123, v143, v123
	v_add_f32_e32 v122, v144, v122
	v_add_f32_e32 v123, v145, v123
	v_cvt_pk_bf16_f32 v114, v138, v139
	v_cvt_pk_bf16_f32 v115, v140, v141
	v_cvt_pk_bf16_f32 v116, v142, v143
	v_cvt_pk_bf16_f32 v117, v144, v145
	v_mfma_f32_32x32x16_bf16 v[154:169], v[106:109], v[2:5], v[154:169]
	ds_read_b128 v[196:199], v91 offset:0
	v_exp_f32_e32 v146, v146
	v_exp_f32_e32 v147, v147
	v_mfma_f32_32x32x16_bf16 v[154:169], v[110:113], v[6:9], v[154:169]
	ds_read_b128 v[216:219], v91 offset:8192
	v_exp_f32_e32 v148, v148
	v_exp_f32_e32 v149, v149
	s_waitcnt lgkmcnt(5)
	v_mfma_f32_32x32x16_bf16 v[18:33], v[128:131], v[114:117], v[18:33]
	v_exp_f32_e32 v150, v150
	v_exp_f32_e32 v151, v151
	s_waitcnt lgkmcnt(4)
	v_mfma_f32_32x32x16_bf16 v[34:49], v[184:187], v[114:117], v[34:49]
	ds_read_b128 v[200:203], v91 offset:16384
	v_exp_f32_e32 v152, v152
	v_exp_f32_e32 v153, v153
	s_waitcnt lgkmcnt(4)
	v_mfma_f32_32x32x16_bf16 v[50:65], v[188:191], v[114:117], v[50:65]
	ds_read_b128 v[204:207], v91 offset:24576
	v_add_f32_e32 v122, v146, v122
	v_add_f32_e32 v123, v147, v123
	v_add_f32_e32 v122, v148, v122
	v_add_f32_e32 v123, v149, v123
	s_waitcnt lgkmcnt(4)
	v_mfma_f32_32x32x16_bf16 v[66:81], v[192:195], v[114:117], v[66:81]
	v_add_f32_e32 v122, v150, v122
	v_add_f32_e32 v123, v151, v123
	v_add_f32_e32 v122, v152, v122
	v_add_f32_e32 v123, v153, v123
	v_cvt_pk_bf16_f32 v118, v146, v147
	v_cvt_pk_bf16_f32 v119, v148, v149
	v_cvt_pk_bf16_f32 v120, v150, v151
	v_cvt_pk_bf16_f32 v121, v152, v153
	s_waitcnt lgkmcnt(3)
	s_nop 0
	v_mfma_f32_32x32x16_bf16 v[18:33], v[196:199], v[118:121], v[18:33]
	ds_read_b128 v[128:131], v92 offset:0
	v_exp_f32_e32 v154, v154
	v_exp_f32_e32 v155, v155
	v_exp_f32_e32 v156, v156
	s_waitcnt lgkmcnt(3)
	v_mfma_f32_32x32x16_bf16 v[34:49], v[216:219], v[118:121], v[34:49]
	ds_read_b128 v[184:187], v92 offset:8192
	v_exp_f32_e32 v157, v157
	v_exp_f32_e32 v158, v158
	v_exp_f32_e32 v159, v159
	v_exp_f32_e32 v160, v160
	s_waitcnt lgkmcnt(3)
	v_mfma_f32_32x32x16_bf16 v[50:65], v[200:203], v[118:121], v[50:65]
	ds_read_b128 v[188:191], v92 offset:16384
	v_exp_f32_e32 v161, v161
	v_add_f32_e32 v122, v154, v122
	v_add_f32_e32 v123, v155, v123
	v_add_f32_e32 v122, v156, v122
	v_add_f32_e32 v123, v157, v123
	v_add_f32_e32 v122, v158, v122
	s_waitcnt lgkmcnt(3)
	v_mfma_f32_32x32x16_bf16 v[66:81], v[204:207], v[118:121], v[66:81]
	ds_read_b128 v[192:195], v92 offset:24576
	v_add_f32_e32 v123, v159, v123
	v_add_f32_e32 v122, v160, v122
	v_add_f32_e32 v123, v161, v123
	v_xor_b32_e32 v82, 0x8000, v82
	v_xor_b32_e32 v83, 0x8000, v83
	v_xor_b32_e32 v84, 0x8000, v84
	v_xor_b32_e32 v85, 0x8000, v85
	v_cvt_pk_bf16_f32 v114, v154, v155
	v_cvt_pk_bf16_f32 v115, v156, v157
	v_cvt_pk_bf16_f32 v116, v158, v159
	v_cvt_pk_bf16_f32 v117, v160, v161
	s_waitcnt lgkmcnt(3)
	s_nop 0
	v_mfma_f32_32x32x16_bf16 v[18:33], v[128:131], v[114:117], v[18:33]
	ds_read_b128 v[196:199], v93 offset:0
	v_exp_f32_e32 v162, v162
	v_exp_f32_e32 v163, v163
	v_exp_f32_e32 v164, v164
	s_waitcnt lgkmcnt(3)
	v_mfma_f32_32x32x16_bf16 v[34:49], v[184:187], v[114:117], v[34:49]
	ds_read_b128 v[216:219], v93 offset:8192
	v_exp_f32_e32 v165, v165
	v_exp_f32_e32 v166, v166
	v_exp_f32_e32 v167, v167
	s_waitcnt lgkmcnt(3)
	v_mfma_f32_32x32x16_bf16 v[50:65], v[188:191], v[114:117], v[50:65]
	ds_read_b128 v[200:203], v93 offset:16384
	v_exp_f32_e32 v168, v168
	v_exp_f32_e32 v169, v169
	v_add_f32_e32 v122, v162, v122
	v_add_f32_e32 v123, v163, v123
	s_waitcnt lgkmcnt(3)
	v_mfma_f32_32x32x16_bf16 v[66:81], v[192:195], v[114:117], v[66:81]
	ds_read_b128 v[204:207], v93 offset:24576
	v_add_f32_e32 v122, v164, v122
	v_add_f32_e32 v123, v165, v123
	v_add_f32_e32 v122, v166, v122
	v_add_f32_e32 v123, v167, v123
	v_add_f32_e32 v122, v168, v122
	v_add_f32_e32 v123, v169, v123
	v_cvt_pk_bf16_f32 v118, v162, v163
	v_cvt_pk_bf16_f32 v119, v164, v165
	v_cvt_pk_bf16_f32 v120, v166, v167
	v_cvt_pk_bf16_f32 v121, v168, v169
	s_waitcnt lgkmcnt(3)
	s_nop 0
	v_mfma_f32_32x32x16_bf16 v[18:33], v[196:199], v[118:121], v[18:33]
	v_xor_b32_e32 v86, 0x8000, v86
	v_xor_b32_e32 v87, 0x8000, v87
	s_waitcnt lgkmcnt(2)
	v_mfma_f32_32x32x16_bf16 v[34:49], v[216:219], v[118:121], v[34:49]
	v_xor_b32_e32 v88, 0x8000, v88
	v_xor_b32_e32 v89, 0x8000, v89
	s_waitcnt lgkmcnt(1)
	v_mfma_f32_32x32x16_bf16 v[50:65], v[200:203], v[118:121], v[50:65]
	v_xor_b32_e32 v90, 0x8000, v90
	v_xor_b32_e32 v91, 0x8000, v91
	s_waitcnt lgkmcnt(0)
	v_mfma_f32_32x32x16_bf16 v[66:81], v[204:207], v[118:121], v[66:81]
	v_xor_b32_e32 v92, 0x8000, v92
	v_xor_b32_e32 v93, 0x8000, v93
	s_waitcnt vmcnt(0)
	s_waitcnt lgkmcnt(0)
	s_barrier
	s_add_i32 s15, s15, 1
	s_cmp_eq_u32 s15, 33
	s_cbranch_scc0 .Lattn_nf_loop
	ds_read_b128 v[98:101], v82 offset:0
	ds_read_b128 v[102:105], v83 offset:0
	ds_read_b128 v[106:109], v84 offset:0
	ds_read_b128 v[110:113], v85 offset:0
	s_waitcnt lgkmcnt(3)
	v_mfma_f32_32x32x16_bf16 v[138:153], v[98:101], v[10:13], 0
	ds_read_b128 v[98:101], v82 offset:8192
	s_waitcnt lgkmcnt(3)
	v_mfma_f32_32x32x16_bf16 v[138:153], v[102:105], v[14:17], v[138:153]
	ds_read_b128 v[102:105], v83 offset:8192
	s_waitcnt lgkmcnt(3)
	v_mfma_f32_32x32x16_bf16 v[138:153], v[106:109], v[2:5], v[138:153]
	ds_read_b128 v[106:109], v84 offset:8192
	s_waitcnt lgkmcnt(3)
	v_mfma_f32_32x32x16_bf16 v[138:153], v[110:113], v[6:9], v[138:153]
	ds_read_b128 v[110:113], v85 offset:8192
	s_waitcnt lgkmcnt(3)
	v_mfma_f32_32x32x16_bf16 v[154:169], v[98:101], v[10:13], 0
	ds_read_b128 v[98:101], v82 offset:16384
	ds_read_b128 v[128:131], v86 offset:0
	ds_read_b128 v[184:187], v86 offset:8192
	s_nop 5
	v_exp_f32_e32 v138, v138
	v_exp_f32_e32 v139, v139
	v_exp_f32_e32 v140, v140
	v_exp_f32_e32 v141, v141
	v_exp_f32_e32 v142, v142
	v_exp_f32_e32 v143, v143
	s_waitcnt lgkmcnt(5)
	v_mfma_f32_32x32x16_bf16 v[154:169], v[102:105], v[14:17], v[154:169]
	ds_read_b128 v[102:105], v83 offset:16384
	ds_read_b128 v[188:191], v86 offset:16384
	ds_read_b128 v[192:195], v86 offset:24576
	v_exp_f32_e32 v144, v144
	v_exp_f32_e32 v145, v145
	v_add_f32_e32 v122, v138, v122
	v_add_f32_e32 v123, v139, v123
	v_add_f32_e32 v122, v140, v122
	v_add_f32_e32 v123, v141, v123
	v_add_f32_e32 v122, v142, v122
	v_add_f32_e32 v123, v143, v123
	v_add_f32_e32 v122, v144, v122
	v_add_f32_e32 v123, v145, v123
	v_cvt_pk_bf16_f32 v114, v138, v139
	v_cvt_pk_bf16_f32 v115, v140, v141
	v_cvt_pk_bf16_f32 v116, v142, v143
	v_cvt_pk_bf16_f32 v117, v144, v145
	s_waitcnt lgkmcnt(7)
	v_mfma_f32_32x32x16_bf16 v[154:169], v[106:109], v[2:5], v[154:169]
	ds_read_b128 v[106:109], v84 offset:16384
	ds_read_b128 v[196:199], v87 offset:0
	v_exp_f32_e32 v146, v146
	v_exp_f32_e32 v147, v147
	s_waitcnt lgkmcnt(8)
	v_mfma_f32_32x32x16_bf16 v[154:169], v[110:113], v[6:9], v[154:169]
	ds_read_b128 v[110:113], v85 offset:16384
	ds_read_b128 v[216:219], v87 offset:8192
	v_exp_f32_e32 v148, v148
	v_exp_f32_e32 v149, v149
	s_waitcnt lgkmcnt(8)
	v_mfma_f32_32x32x16_bf16 v[18:33], v[128:131], v[114:117], v[18:33]
	v_exp_f32_e32 v150, v150
	v_exp_f32_e32 v151, v151
	s_waitcnt lgkmcnt(7)
	v_mfma_f32_32x32x16_bf16 v[34:49], v[184:187], v[114:117], v[34:49]
	ds_read_b128 v[200:203], v87 offset:16384
	v_exp_f32_e32 v152, v152
	v_exp_f32_e32 v153, v153
	s_waitcnt lgkmcnt(6)
	v_mfma_f32_32x32x16_bf16 v[50:65], v[188:191], v[114:117], v[50:65]
	ds_read_b128 v[204:207], v87 offset:24576
	v_add_f32_e32 v122, v146, v122
	v_add_f32_e32 v123, v147, v123
	v_add_f32_e32 v122, v148, v122
	v_add_f32_e32 v123, v149, v123
	s_waitcnt lgkmcnt(6)
	v_mfma_f32_32x32x16_bf16 v[66:81], v[192:195], v[114:117], v[66:81]
	v_add_f32_e32 v122, v150, v122
	v_add_f32_e32 v123, v151, v123
	v_add_f32_e32 v122, v152, v122
	v_add_f32_e32 v123, v153, v123
	v_cvt_pk_bf16_f32 v118, v146, v147
	v_cvt_pk_bf16_f32 v119, v148, v149
	v_cvt_pk_bf16_f32 v120, v150, v151
	v_cvt_pk_bf16_f32 v121, v152, v153
	v_mfma_f32_32x32x16_bf16 v[138:153], v[98:101], v[10:13], 0
	ds_read_b128 v[98:101], v82 offset:24576
	ds_read_b128 v[128:131], v88 offset:0
	v_exp_f32_e32 v154, v154
	v_exp_f32_e32 v155, v155
	v_mfma_f32_32x32x16_bf16 v[138:153], v[102:105], v[14:17], v[138:153]
	ds_read_b128 v[102:105], v83 offset:24576
	ds_read_b128 v[184:187], v88 offset:8192
	v_exp_f32_e32 v156, v156
	v_exp_f32_e32 v157, v157
	s_waitcnt lgkmcnt(8)
	v_mfma_f32_32x32x16_bf16 v[18:33], v[196:199], v[118:121], v[18:33]
	v_exp_f32_e32 v158, v158
	v_exp_f32_e32 v159, v159
	s_waitcnt lgkmcnt(6)
	v_mfma_f32_32x32x16_bf16 v[34:49], v[216:219], v[118:121], v[34:49]
	ds_read_b128 v[188:191], v88 offset:16384
	v_exp_f32_e32 v160, v160
	v_exp_f32_e32 v161, v161
	s_waitcnt lgkmcnt(6)
	v_mfma_f32_32x32x16_bf16 v[50:65], v[200:203], v[118:121], v[50:65]
	ds_read_b128 v[192:195], v88 offset:24576
	v_add_f32_e32 v122, v154, v122
	v_add_f32_e32 v123, v155, v123
	v_add_f32_e32 v122, v156, v122
	v_add_f32_e32 v123, v157, v123
	s_waitcnt lgkmcnt(6)
	v_mfma_f32_32x32x16_bf16 v[66:81], v[204:207], v[118:121], v[66:81]
	v_add_f32_e32 v122, v158, v122
	v_add_f32_e32 v123, v159, v123
	v_add_f32_e32 v122, v160, v122
	v_add_f32_e32 v123, v161, v123
	v_cvt_pk_bf16_f32 v114, v154, v155
	v_cvt_pk_bf16_f32 v115, v156, v157
	v_cvt_pk_bf16_f32 v116, v158, v159
	v_cvt_pk_bf16_f32 v117, v160, v161
	v_mfma_f32_32x32x16_bf16 v[138:153], v[106:109], v[2:5], v[138:153]
	ds_read_b128 v[106:109], v84 offset:24576
	ds_read_b128 v[196:199], v89 offset:0
	v_exp_f32_e32 v162, v162
	v_exp_f32_e32 v163, v163
	v_mfma_f32_32x32x16_bf16 v[138:153], v[110:113], v[6:9], v[138:153]
	ds_read_b128 v[110:113], v85 offset:24576
	ds_read_b128 v[216:219], v89 offset:8192
	v_exp_f32_e32 v164, v164
	v_exp_f32_e32 v165, v165
	s_waitcnt lgkmcnt(8)
	v_mfma_f32_32x32x16_bf16 v[18:33], v[128:131], v[114:117], v[18:33]
	v_exp_f32_e32 v166, v166
	v_exp_f32_e32 v167, v167
	s_waitcnt lgkmcnt(6)
	v_mfma_f32_32x32x16_bf16 v[34:49], v[184:187], v[114:117], v[34:49]
	ds_read_b128 v[200:203], v89 offset:16384
	v_exp_f32_e32 v168, v168
	v_exp_f32_e32 v169, v169
	s_waitcnt lgkmcnt(6)
	v_mfma_f32_32x32x16_bf16 v[50:65], v[188:191], v[114:117], v[50:65]
	ds_read_b128 v[204:207], v89 offset:24576
	v_add_f32_e32 v122, v162, v122
	v_add_f32_e32 v123, v163, v123
	v_add_f32_e32 v122, v164, v122
	v_add_f32_e32 v123, v165, v123
	s_waitcnt lgkmcnt(6)
	v_mfma_f32_32x32x16_bf16 v[66:81], v[192:195], v[114:117], v[66:81]
	v_add_f32_e32 v122, v166, v122
	v_add_f32_e32 v123, v167, v123
	v_add_f32_e32 v122, v168, v122
	v_add_f32_e32 v123, v169, v123
	v_cvt_pk_bf16_f32 v118, v162, v163
	v_cvt_pk_bf16_f32 v119, v164, v165
	v_cvt_pk_bf16_f32 v120, v166, v167
	v_cvt_pk_bf16_f32 v121, v168, v169
	v_mfma_f32_32x32x16_bf16 v[154:169], v[98:101], v[10:13], 0
	ds_read_b128 v[128:131], v90 offset:0
	v_exp_f32_e32 v138, v138
	v_exp_f32_e32 v139, v139
	v_mfma_f32_32x32x16_bf16 v[154:169], v[102:105], v[14:17], v[154:169]
	ds_read_b128 v[184:187], v90 offset:8192
	v_exp_f32_e32 v140, v140
	v_exp_f32_e32 v141, v141
	s_waitcnt lgkmcnt(6)
	v_mfma_f32_32x32x16_bf16 v[18:33], v[196:199], v[118:121], v[18:33]
	v_exp_f32_e32 v142, v142
	v_exp_f32_e32 v143, v143
	s_waitcnt lgkmcnt(4)
	v_mfma_f32_32x32x16_bf16 v[34:49], v[216:219], v[118:121], v[34:49]
	ds_read_b128 v[188:191], v90 offset:16384
	v_exp_f32_e32 v144, v144
	v_exp_f32_e32 v145, v145
	s_waitcnt lgkmcnt(4)
	v_mfma_f32_32x32x16_bf16 v[50:65], v[200:203], v[118:121], v[50:65]
	ds_read_b128 v[192:195], v90 offset:24576
	v_add_f32_e32 v122, v138, v122
	v_add_f32_e32 v123, v139, v123
	v_add_f32_e32 v122, v140, v122
	v_add_f32_e32 v123, v141, v123
	s_waitcnt lgkmcnt(4)
	v_mfma_f32_32x32x16_bf16 v[66:81], v[204:207], v[118:121], v[66:81]
	v_add_f32_e32 v122, v142, v122
	v_add_f32_e32 v123, v143, v123
	v_add_f32_e32 v122, v144, v122
	v_add_f32_e32 v123, v145, v123
	v_cvt_pk_bf16_f32 v114, v138, v139
	v_cvt_pk_bf16_f32 v115, v140, v141
	v_cvt_pk_bf16_f32 v116, v142, v143
	v_cvt_pk_bf16_f32 v117, v144, v145
	v_mfma_f32_32x32x16_bf16 v[154:169], v[106:109], v[2:5], v[154:169]
	ds_read_b128 v[196:199], v91 offset:0
	v_exp_f32_e32 v146, v146
	v_exp_f32_e32 v147, v147
	v_mfma_f32_32x32x16_bf16 v[154:169], v[110:113], v[6:9], v[154:169]
	ds_read_b128 v[216:219], v91 offset:8192
	v_exp_f32_e32 v148, v148
	v_exp_f32_e32 v149, v149
	s_waitcnt lgkmcnt(5)
	v_mfma_f32_32x32x16_bf16 v[18:33], v[128:131], v[114:117], v[18:33]
	v_exp_f32_e32 v150, v150
	v_exp_f32_e32 v151, v151
	s_waitcnt lgkmcnt(4)
	v_mfma_f32_32x32x16_bf16 v[34:49], v[184:187], v[114:117], v[34:49]
	ds_read_b128 v[200:203], v91 offset:16384
	v_exp_f32_e32 v152, v152
	v_exp_f32_e32 v153, v153
	s_waitcnt lgkmcnt(4)
	v_mfma_f32_32x32x16_bf16 v[50:65], v[188:191], v[114:117], v[50:65]
	ds_read_b128 v[204:207], v91 offset:24576
	v_add_f32_e32 v122, v146, v122
	v_add_f32_e32 v123, v147, v123
	v_add_f32_e32 v122, v148, v122
	v_add_f32_e32 v123, v149, v123
	s_waitcnt lgkmcnt(4)
	v_mfma_f32_32x32x16_bf16 v[66:81], v[192:195], v[114:117], v[66:81]
	v_add_f32_e32 v122, v150, v122
	v_add_f32_e32 v123, v151, v123
	v_add_f32_e32 v122, v152, v122
	v_add_f32_e32 v123, v153, v123
	v_cvt_pk_bf16_f32 v118, v146, v147
	v_cvt_pk_bf16_f32 v119, v148, v149
	v_cvt_pk_bf16_f32 v120, v150, v151
	v_cvt_pk_bf16_f32 v121, v152, v153
	s_waitcnt lgkmcnt(3)
	s_nop 0
	v_mfma_f32_32x32x16_bf16 v[18:33], v[196:199], v[118:121], v[18:33]
	ds_read_b128 v[128:131], v92 offset:0
	v_exp_f32_e32 v154, v154
	v_exp_f32_e32 v155, v155
	v_exp_f32_e32 v156, v156
	s_waitcnt lgkmcnt(3)
	v_mfma_f32_32x32x16_bf16 v[34:49], v[216:219], v[118:121], v[34:49]
	ds_read_b128 v[184:187], v92 offset:8192
	v_exp_f32_e32 v157, v157
	v_exp_f32_e32 v158, v158
	v_exp_f32_e32 v159, v159
	s_waitcnt lgkmcnt(3)
	v_mfma_f32_32x32x16_bf16 v[50:65], v[200:203], v[118:121], v[50:65]
	ds_read_b128 v[188:191], v92 offset:16384
	v_exp_f32_e32 v160, v160
	v_exp_f32_e32 v161, v161
	v_add_f32_e32 v122, v154, v122
	v_add_f32_e32 v123, v155, v123
	s_waitcnt lgkmcnt(3)
	v_mfma_f32_32x32x16_bf16 v[66:81], v[204:207], v[118:121], v[66:81]
	ds_read_b128 v[192:195], v92 offset:24576
	v_add_f32_e32 v122, v156, v122
	v_add_f32_e32 v123, v157, v123
	v_add_f32_e32 v122, v158, v122
	v_add_f32_e32 v123, v159, v123
	v_add_f32_e32 v122, v160, v122
	v_add_f32_e32 v123, v161, v123
	v_cvt_pk_bf16_f32 v114, v154, v155
	v_cvt_pk_bf16_f32 v115, v156, v157
	v_cvt_pk_bf16_f32 v116, v158, v159
	v_cvt_pk_bf16_f32 v117, v160, v161
	s_waitcnt lgkmcnt(3)
	s_nop 0
	v_mfma_f32_32x32x16_bf16 v[18:33], v[128:131], v[114:117], v[18:33]
	ds_read_b128 v[196:199], v93 offset:0
	v_exp_f32_e32 v162, v162
	v_exp_f32_e32 v163, v163
	v_exp_f32_e32 v164, v164
	s_waitcnt lgkmcnt(3)
	v_mfma_f32_32x32x16_bf16 v[34:49], v[184:187], v[114:117], v[34:49]
	ds_read_b128 v[216:219], v93 offset:8192
	v_exp_f32_e32 v165, v165
	v_exp_f32_e32 v166, v166
	v_exp_f32_e32 v167, v167
	s_waitcnt lgkmcnt(3)
	v_mfma_f32_32x32x16_bf16 v[50:65], v[188:191], v[114:117], v[50:65]
	ds_read_b128 v[200:203], v93 offset:16384
	v_exp_f32_e32 v168, v168
	v_exp_f32_e32 v169, v169
	v_add_f32_e32 v122, v162, v122
	v_add_f32_e32 v123, v163, v123
	s_waitcnt lgkmcnt(3)
	v_mfma_f32_32x32x16_bf16 v[66:81], v[192:195], v[114:117], v[66:81]
	ds_read_b128 v[204:207], v93 offset:24576
	v_add_f32_e32 v122, v164, v122
	v_add_f32_e32 v123, v165, v123
	v_add_f32_e32 v122, v166, v122
	v_add_f32_e32 v123, v167, v123
	v_add_f32_e32 v122, v168, v122
	v_add_f32_e32 v123, v169, v123
	v_cvt_pk_bf16_f32 v118, v162, v163
	v_cvt_pk_bf16_f32 v119, v164, v165
	v_cvt_pk_bf16_f32 v120, v166, v167
	v_cvt_pk_bf16_f32 v121, v168, v169
	s_waitcnt lgkmcnt(3)
	s_nop 0
	v_mfma_f32_32x32x16_bf16 v[18:33], v[196:199], v[118:121], v[18:33]
	s_waitcnt lgkmcnt(2)
	v_mfma_f32_32x32x16_bf16 v[34:49], v[216:219], v[118:121], v[34:49]
	s_waitcnt lgkmcnt(1)
	v_mfma_f32_32x32x16_bf16 v[50:65], v[200:203], v[118:121], v[50:65]
	s_waitcnt lgkmcnt(0)
	v_mfma_f32_32x32x16_bf16 v[66:81], v[204:207], v[118:121], v[66:81]
	s_waitcnt vmcnt(0)
	s_waitcnt lgkmcnt(0)
	s_barrier
	v_readlane_b32 s64, v175, 0
	v_readlane_b32 s65, v175, 1
	v_readlane_b32 s66, v175, 2
	v_readlane_b32 s67, v175, 3
	v_readlane_b32 s68, v175, 4
	v_readlane_b32 s69, v175, 5
	v_readlane_b32 s70, v175, 6
	v_readlane_b32 s71, v175, 7
	v_readlane_b32 s72, v175, 8
	v_readlane_b32 s73, v175, 9
	v_readlane_b32 s74, v175, 10
	v_readlane_b32 s75, v175, 11
	v_readlane_b32 s76, v175, 12
	v_readlane_b32 s77, v175, 13
	v_readlane_b32 s78, v175, 14
	v_readlane_b32 s79, v175, 15
	s_nop 4
	s_mov_b32 s10, 0x3fb8aa3b
	s_mov_b32 s11, 0xc2ce8ed0
	s_mov_b32 s6, 0x42b17218
	v_cmp_eq_u32_e64 s[40:41], 0, v179
	s_lshl_b32 s30, s14, 1
	v_lshlrev_b32_e32 v196, 3, v178
	v_mov_b32_e32 v197, 0
	v_lshlrev_b32_e32 v198, 4, v179
	v_or3_b32 v198, v198, v177, v180
	v_ashrrev_i32_e32 v199, 31, v198
	v_lshlrev_b64 v[198:199], 11, v[198:199]
	s_mov_b64 s[100:101], 0x18a10000
	v_lshl_add_u64 v[198:199], s[42:43], 0, v[198:199]
	v_lshl_add_u64 v[198:199], v[198:199], 0, s[30:31]
	v_lshl_add_u64 v[198:199], v[198:199], 0, v[196:197]
	v_lshl_add_u64 v[198:199], v[198:199], 0, s[100:101]
	global_load_dwordx2 v[146:147], v[198:199], off
	global_load_dwordx2 v[148:149], v[198:199], off offset:32
	global_load_dwordx2 v[150:151], v[198:199], off offset:64
	global_load_dwordx2 v[152:153], v[198:199], off offset:96
	global_load_dwordx2 v[188:189], v[198:199], off offset:128
	global_load_dwordx2 v[190:191], v[198:199], off offset:160
	global_load_dwordx2 v[192:193], v[198:199], off offset:192
	global_load_dwordx2 v[194:195], v[198:199], off offset:224
	s_mov_b64 s[100:101], exec
	s_and_b64 exec, exec, s[4:5]
	s_cbranch_execz .Lpop_skip
	v_readlane_b32 s14, v255, 22
	v_readlane_b32 s15, v255, 23
	v_mov_b32_e32 v224, 1
	s_nop 4
	global_atomic_add v224, v0, v224, s[14:15] sc0
